# v31 + P2 queue: after popping a gate item (64..95) waves 4-7 touch a 256 KiB chunk of the XCD's x_prompt region (LLC warm for P3's residual reads)
# baseline (speedup 1.0000x reference)
.LBB0_404:
	s_or_b64 exec, exec, s[2:3]
	s_waitcnt lgkmcnt(0)
	s_barrier
	ds_read_b32 v2, v243
	s_movk_i32 s1, 0x5f
	s_mov_b64 s[2:3], -1
	s_waitcnt lgkmcnt(0)
	s_barrier
	v_cmp_lt_i32_e32 vcc, s1, v2
	v_readfirstlane_b32 s8, v2
	v_readfirstlane_b32 s98, v0
	s_cmp_lt_u32 s98, 256
	s_cbranch_scc1 .Lmy_x3_skip
	s_cmp_lt_i32 s8, 64
	s_cbranch_scc1 .Lmy_x3_skip
	s_cmp_gt_i32 s8, 95
	s_cbranch_scc1 .Lmy_x3_skip
	v_readlane_b32 s98, v251, 63
	s_and_b32 s98, s98, 7
	s_lshl_b32 s98, s98, 23
	s_sub_i32 s99, s8, 64
	s_lshl_b32 s99, s99, 18
	s_add_u32 s98, s98, s99
	s_add_u32 s98, s76, s98
	s_addc_u32 s99, s77, 0
	v_add_u32_e32 v252, 0xffffff00, v0
	v_lshlrev_b32_e32 v252, 7, v252
	s_nop 1
	global_load_dword v255, v252, s[98:99]
	v_add_u32_e32 v253, 0x8000, v252
	global_load_dword v255, v253, s[98:99]
	v_add_u32_e32 v253, 0x10000, v252
	global_load_dword v255, v253, s[98:99]
	v_add_u32_e32 v253, 0x18000, v252
	global_load_dword v255, v253, s[98:99]
	v_add_u32_e32 v253, 0x20000, v252
	global_load_dword v255, v253, s[98:99]
	v_add_u32_e32 v253, 0x28000, v252
	global_load_dword v255, v253, s[98:99]
	v_add_u32_e32 v253, 0x30000, v252
	global_load_dword v255, v253, s[98:99]
	v_add_u32_e32 v253, 0x38000, v252
	global_load_dword v255, v253, s[98:99]
.Lmy_x3_skip:
	s_cbranch_vccnz .LBB0_399
	s_cmp_gt_i32 s8, 63
	s_cbranch_scc0 .LBB0_415
	s_lshl_b32 s2, s8, 1
	v_readlane_b32 s1, v251, 53
	s_add_i32 s1, s1, s2
	v_readlane_b32 s3, v250, 8
	s_add_i32 s2, s3, s2
	s_lshl_b32 s3, s1, 5
	s_lshl_b32 s9, s1, 7
	s_branch .LBB0_408
